# resid phases: residual-row (Pre) loads issued after the prologue LDS-DMA pieces instead of before them; prologue/preheader waits recounted (vmcnt(18), first-tile vmcnt(12))
# speedup vs baseline: 1.0029x; 1.0029x over previous
.LBB0_1005:
	s_andn2_b64 vcc, exec, s[44:45]
	s_cbranch_vccnz .LBB0_1168
	v_bfe_i32 v3, v0, 27, 1
	v_lshlrev_b32_e32 v1, 4, v0
	v_lshrrev_b32_e32 v3, 22, v3
	v_add_u32_e32 v3, v1, v3
	v_and_b32_e32 v3, 0xfffffc00, v3
	v_ashrrev_i32_e32 v2, 31, v0
	v_sub_u32_e32 v3, v1, v3
	v_lshrrev_b32_e32 v2, 26, v2
	s_waitcnt vmcnt(8)
	v_lshrrev_b32_e32 v4, 4, v3
	v_add_u32_e32 v2, v0, v2
	v_bitop3_b32 v4, v4, v3, 32 bitop3:0x6c
	v_ashrrev_i32_e32 v3, 31, v3
	v_ashrrev_i32_e32 v2, 6, v2
	v_lshrrev_b32_e32 v3, 26, v3
	v_lshlrev_b32_e32 v5, 3, v2
	v_add_u32_e32 v3, v4, v3
	v_and_b32_e32 v5, -16, v5
	v_ashrrev_i32_e32 v3, 6, v3
	v_lshlrev_b32_e32 v2, 5, v2
	v_add_u32_e32 v5, v3, v5
	s_waitcnt vmcnt(2)
	v_and_b32_e32 v29, 32, v2
	v_mul_i32_i24_e32 v2, 64, v3
	v_sub_u32_e32 v2, v4, v2
	v_mov_b32_e32 v7, 1
	v_lshlrev_b32_e32 v4, 1, v5
	v_lshrrev_b32_e32 v6, 2, v5
	v_and_b32_e32 v3, 3, v3
	s_mov_b32 s4, 0x7fffffe0
	v_ashrrev_i16_sdwa v2, v7, sext(v2) dst_sel:DWORD dst_unused:UNUSED_PAD src0_sel:DWORD src1_sel:BYTE_0
	v_and_b32_e32 v4, 24, v4
	v_and_b32_e32 v6, 4, v6
	v_and_or_b32 v3, v5, s4, v3
	v_bfe_i32 v30, v2, 0, 16
	v_or3_b32 v3, v3, v6, v4
	v_add_u32_e32 v2, v29, v30
	v_mul_lo_u32 v31, v5, s2
	v_mul_lo_u32 v3, v3, s27
	v_add_u32_e32 v1, 0x2000, v1
	v_add_lshl_u32 v176, v2, v31, 1
	v_add_lshl_u32 v182, v3, v2, 1
	v_ashrrev_i32_e32 v2, 31, v1
	v_lshrrev_b32_e32 v2, 22, v2
	v_add_u32_e32 v2, v1, v2
	v_ashrrev_i32_e32 v2, 10, v2
	v_mul_i32_i24_e32 v3, 0x400, v2
	v_sub_u32_e32 v1, v1, v3
	v_lshrrev_b32_e32 v3, 4, v1
	v_bitop3_b32 v1, v3, v1, 32 bitop3:0x6c
	v_ashrrev_i32_e32 v4, 31, v1
	v_lshrrev_b32_e32 v4, 26, v4
	v_lshlrev_b32_e32 v3, 3, v2
	v_add_u32_e32 v4, v1, v4
	v_and_b32_e32 v3, -16, v3
	v_ashrrev_i32_e32 v5, 6, v4
	v_lshlrev_b32_e32 v2, 5, v2
	s_add_u32 s62, s48, 0x57c8000
	v_add_u32_e32 v3, v5, v3
	s_waitcnt vmcnt(1)
	v_and_b32_e32 v40, 32, v2
	v_and_b32_e32 v2, 0xc0, v4
	s_addc_u32 s63, s49, 0
	v_sub_u32_e32 v1, v1, v2
	v_lshlrev_b32_e32 v2, 1, v3
	v_lshrrev_b32_e32 v4, 2, v3
	v_and_b32_e32 v5, 3, v5
	s_ashr_i32 s43, s39, 8
	s_ashr_i32 s3, s39, 6
	v_ashrrev_i16_sdwa v1, v7, sext(v1) dst_sel:DWORD dst_unused:UNUSED_PAD src0_sel:DWORD src1_sel:BYTE_0
	v_and_b32_e32 v2, 24, v2
	v_and_b32_e32 v4, 4, v4
	v_and_or_b32 v5, v3, s4, v5
	v_mul_lo_u32 v42, v3, s2
	s_mul_i32 s64, s2, 0xc0
	s_mul_i32 s19, s43, 48
	s_mul_i32 s2, s86, 0xc0
	s_and_b32 s56, s3, 3
	v_bfe_i32 v41, v1, 0, 16
	v_or3_b32 v2, v5, v4, v2
	v_and_b32_e32 v223, 15, v0
	s_add_i32 s2, s2, s19
	v_bfe_u32 v28, v0, 4, 2
	v_add_u32_e32 v1, v40, v41
	v_mul_lo_u32 v2, v2, s27
	s_lshl_b32 s28, s56, 5
	v_or_b32_e32 v0, s2, v223
	s_lshl_b32 s2, s72, 8
	v_add_lshl_u32 v184, v1, v42, 1
	v_add_lshl_u32 v186, v2, v1, 1
	v_lshlrev_b32_e32 v43, 3, v28
	s_or_b32 s2, s2, s28
	v_ashrrev_i32_e32 v1, 31, v0
	v_or_b32_e32 v2, s2, v43
	v_lshlrev_b64 v[0:1], 11, v[0:1]
	v_ashrrev_i32_e32 v3, 31, v2
	v_lshl_add_u64 v[0:1], s[62:63], 0, v[0:1]
	v_lshl_add_u64 v[0:1], v[2:3], 1, v[0:1]
	s_lshl_b32 s18, s3, 10
	s_ashr_i32 s2, s72, 31
	s_lshl_b32 s11, s27, 9
	s_mul_hi_u32 s5, s60, s72
	s_mul_i32 s37, s60, s2
	s_add_i32 s5, s5, s37
	s_mul_i32 s37, s61, s72
	s_mul_i32 s2, s11, s2
	s_mul_hi_u32 s44, s11, s72
	s_lshl_b32 s57, s27, 8
	s_lshl_b32 s10, s64, 1
	s_add_i32 s5, s5, s37
	s_add_i32 s44, s44, s2
	s_mul_i32 s2, s11, s72
	s_add_u32 s46, s52, s2
	s_addc_u32 s47, s53, s44
	s_add_i32 s2, s18, 0
	s_add_i32 m0, s2, 0x10000
	s_mul_i32 s4, s10, s86
	global_load_lds_dwordx4 v182, s[46:47]
	s_add_i32 m0, s2, 0x12000
	s_mul_hi_i32 s3, s10, s86
	s_add_u32 s4, s50, s4
	s_mul_i32 s37, s60, s72
	s_addc_u32 s3, s51, s3
	s_add_u32 s84, s4, s37
	global_load_lds_dwordx4 v186, s[46:47]
	s_addc_u32 s85, s3, s5
	s_mov_b32 m0, s2
	s_add_i32 s3, s2, 0x2000
	global_load_lds_dwordx4 v176, s[84:85]
	s_mov_b32 m0, s3
	s_add_u32 s4, s46, s57
	global_load_lds_dwordx4 v184, s[84:85]
	s_addc_u32 s5, s47, 0
	s_add_i32 m0, s2, 0x14000
	v_mov_b32_e32 v183, v97
	global_load_lds_dwordx4 v182, s[4:5]
	s_add_i32 m0, s2, 0x16000
	v_mov_b32_e32 v187, v97
	s_add_u32 s44, s84, s64
	v_lshl_add_u64 v[24:25], s[4:5], 0, v[182:183]
	v_lshl_add_u64 v[26:27], s[4:5], 0, v[186:187]
	global_load_lds_dwordx4 v186, s[4:5]
	s_addc_u32 s45, s85, 0
	s_add_i32 s4, s2, 0x4000
	s_mov_b32 m0, s4
	s_add_i32 s5, s2, 0x6000
	global_load_lds_dwordx4 v176, s[44:45]
	s_mov_b32 m0, s5
	v_mov_b32_e32 v177, v97
	global_load_lds_dwordx4 v184, s[44:45]
	v_mov_b32_e32 v185, v97
	v_mov_b32_e32 v222, 9
	s_mov_b32 s65, s73
	v_lshl_add_u64 v[16:17], s[46:47], 0, v[182:183]
	v_lshl_add_u64 v[18:19], s[46:47], 0, v[186:187]
	v_lshl_add_u64 v[20:21], s[84:85], 0, v[176:177]
	v_lshl_add_u64 v[22:23], s[84:85], 0, v[184:185]
	s_cmp_lg_u32 s43, 1
	s_cbranch_scc1 .LBB0_1008
	s_barrier
.LBB0_1008:
	s_mul_i32 s44, s97, 0x12000
	s_mul_hi_u32 s37, s97, 0x12000
	s_add_u32 s44, s48, s44
	s_addc_u32 s37, s49, s37
	s_add_u32 s66, s44, s40
	s_addc_u32 s67, s37, s41
	s_add_u32 s68, s48, 0x87c8000
	s_addc_u32 s69, s49, 0
	s_lshl_b32 s40, s42, 2
	s_add_u32 s70, s44, s40
	s_addc_u32 s71, s37, 0
	s_add_u32 s74, s48, 0x13648000
	s_addc_u32 s75, s49, 0
	s_lshr_b32 s37, s27, 6
	s_lshl_b32 s27, s56, 12
	s_cmp_lg_u32 s36, 7
	s_cselect_b64 s[76:77], -1, 0
	s_add_i32 m0, s2, 0x18000
	v_lshl_add_u64 v[16:17], v[16:17], 0, s[6:7]
	s_waitcnt vmcnt(4)
	s_barrier
	global_load_lds_dwordx4 v[16:17], off
	v_lshl_add_u64 v[16:17], v[18:19], 0, s[6:7]
	s_add_i32 m0, s2, 0x1a000
	s_add_i32 s88, s2, 0x8000
	global_load_lds_dwordx4 v[16:17], off
	v_lshl_add_u64 v[16:17], v[20:21], 0, s[6:7]
	s_mov_b32 m0, s88
	s_add_i32 s89, s2, 0xa000
	global_load_lds_dwordx4 v[16:17], off
	v_lshl_add_u64 v[16:17], v[22:23], 0, s[6:7]
	s_mov_b32 m0, s89
	v_or_b32_e32 v224, s19, v223
	global_load_lds_dwordx4 v[16:17], off
	s_add_i32 m0, s2, 0x1c000
	v_lshl_add_u64 v[16:17], v[24:25], 0, s[6:7]
	global_load_lds_dwordx4 v[16:17], off
	v_lshl_add_u64 v[16:17], v[26:27], 0, s[6:7]
	s_add_i32 m0, s2, 0x1e000
	s_movk_i32 s29, 0x3c0
	global_load_lds_dwordx4 v[16:17], off
	s_mov_b32 s100, 0x8000
	v_add_co_u32_e32 v4, vcc, s100, v0
	v_lshl_add_u64 v[2:3], v[0:1], 0, s[12:13]
	v_addc_co_u32_e32 v5, vcc, 0, v1, vcc
	s_mov_b64 s[100:101], 0x10000
	global_load_dwordx4 v[140:143], v[0:1], off
	global_load_dwordx4 v[136:139], v[0:1], off offset:256
	global_load_dwordx4 v[108:111], v[4:5], off
	global_load_dwordx4 v[92:95], v[2:3], off offset:256
	v_lshl_add_u64 v[2:3], v[0:1], 0, s[100:101]
	s_mov_b32 s100, 0x10000
	v_add_co_u32_e32 v4, vcc, s100, v0
	s_mov_b64 s[100:101], 0x30000
	s_nop 0
	v_addc_co_u32_e32 v5, vcc, 0, v1, vcc
	global_load_dwordx4 v[64:67], v[4:5], off
	global_load_dwordx4 v[60:63], v[2:3], off offset:256
	v_lshl_add_u64 v[2:3], v[0:1], 0, s[100:101]
	s_mov_b32 s100, 0x30000
	v_add_co_u32_e32 v4, vcc, s100, v0
	s_mov_b64 s[100:101], 0x38000
	s_nop 0
	v_addc_co_u32_e32 v5, vcc, 0, v1, vcc
	global_load_dwordx4 v[36:39], v[4:5], off
	global_load_dwordx4 v[32:35], v[2:3], off offset:256
	v_lshl_add_u64 v[2:3], v[0:1], 0, s[100:101]
	s_mov_b32 s100, 0x38000
	v_add_co_u32_e32 v4, vcc, s100, v0
	s_mov_b64 s[100:101], 0x40000
	s_nop 0
	v_addc_co_u32_e32 v5, vcc, 0, v1, vcc
	global_load_dwordx4 v[12:15], v[4:5], off
	global_load_dwordx4 v[8:11], v[2:3], off offset:256
	v_lshl_add_u64 v[2:3], v[0:1], 0, s[100:101]
	s_mov_b32 s100, 0x40000
	v_add_co_u32_e32 v0, vcc, s100, v0
	s_nop 1
	v_addc_co_u32_e32 v1, vcc, 0, v1, vcc
	global_load_dwordx4 v[4:7], v[0:1], off
	s_nop 0
	global_load_dwordx4 v[0:3], v[2:3], off offset:256
	v_lshlrev_b32_e32 v16, 6, v224
	v_lshlrev_b32_e32 v17, 4, v28
	v_lshlrev_b32_e32 v18, 2, v224
	v_and_or_b32 v16, v16, s29, v17
	s_mulk_i32 s43, 0x1800
	v_and_b32_e32 v18, 32, v18
	v_bitop3_b32 v16, v16, s43, v18 bitop3:0xde
	v_lshlrev_b32_e32 v18, 2, v223
	v_lshl_or_b32 v17, v223, 6, v17
	v_and_b32_e32 v18, 32, v18
	v_bitop3_b32 v225, v17, s27, v18 bitop3:0xde
	v_add_u32_e32 v17, v31, v29
	s_waitcnt vmcnt(18)
	s_add_i32 s90, s37, -2
	s_ashr_i32 s27, s38, 31
	v_add_lshl_u32 v96, v17, v30, 1
	v_add_u32_e32 v17, v42, v40
	s_cmp_lg_u64 s[54:55], 0
	v_lshl_add_u64 v[188:189], s[64:65], 0, v[96:97]
	v_add_lshl_u32 v96, v17, v41, 1
	s_mov_b32 s91, 0
	v_cmp_eq_u32_e64 s[40:41], 0, v28
	s_cselect_b64 s[78:79], -1, 0
	v_or_b32_e32 v226, s28, v43
	v_lshl_add_u64 v[190:191], s[64:65], 0, v[96:97]
	v_add_u32_e32 v227, 0, v16
	s_barrier
	s_branch .LBB0_1010

.LBB0_1020:
	s_add_u32 s44, s84, 0x80
	s_addc_u32 s45, s85, 0
	s_add_u32 s87, s46, 0x100
	s_addc_u32 vcc_lo, s47, 0
	s_mov_b32 s46, 0
	s_cmp_eq_u32 s91, 1
	s_cbranch_scc1 .Lrs_first_tile
	s_waitcnt vmcnt(0)
.Lrs_first_tile:
	s_waitcnt vmcnt(12)
	v_add_u32_e32 v96, 0x10000, v225
	ds_read_b128 v[80:83], v96 offset:2048
	ds_read_b128 v[98:101], v96 offset:3072
	s_add_i32 vcc_hi, s46, 2
	s_add_u32 s84, s44, 0x80
	s_addc_u32 s47, s45, 0
	s_add_i32 s29, 0, 0x10000
	v_add_u32_e32 v96, s29, v225
	ds_read_b128 v[56:59], v96
	ds_read_b128 v[68:71], v96 offset:1024
	s_cmp_eq_u32 s90, s46
	s_cselect_b32 s46, s80, s84
	s_cselect_b32 s47, s81, s47
	s_cselect_b32 s85, s83, vcc_lo
	s_cselect_b32 s84, s82, s87
	s_add_i32 m0, s2, 0xc000
	ds_read_b128 v[102:105], v227
	ds_read_b128 v[112:115], v227 offset:1024
	ds_read_b128 v[124:127], v227 offset:2048
	ds_read_b128 v[192:195], v227 offset:3072
	ds_read_b128 v[196:199], v227 offset:4096
	ds_read_b128 v[200:203], v227 offset:5120
	global_load_lds_dwordx4 v188, s[44:45]
	s_add_i32 m0, s2, 0xe000
	s_mov_b64 exec, s[98:99]
	global_load_lds_dwordx4 v190, s[44:45]
	s_mov_b64 exec, -1
	s_waitcnt lgkmcnt(6)
	s_setprio 1
	s_barrier
	s_waitcnt lgkmcnt(0)
	v_mfma_f32_16x16x32_bf16 v[172:175], v[56:59], v[102:105], 0
	v_mfma_f32_16x16x32_bf16 v[168:171], v[80:83], v[102:105], 0
	v_mfma_f32_16x16x32_bf16 v[156:159], v[56:59], v[124:127], 0
	v_mfma_f32_16x16x32_bf16 v[152:155], v[80:83], v[124:127], 0
	v_mfma_f32_16x16x32_bf16 v[132:135], v[56:59], v[196:199], 0
	v_mfma_f32_16x16x32_bf16 v[128:131], v[80:83], v[196:199], 0
	v_mfma_f32_16x16x32_bf16 v[172:175], v[68:71], v[112:115], v[172:175]
	v_mfma_f32_16x16x32_bf16 v[168:171], v[98:101], v[112:115], v[168:171]
	v_mfma_f32_16x16x32_bf16 v[156:159], v[68:71], v[192:195], v[156:159]
	v_mfma_f32_16x16x32_bf16 v[152:155], v[98:101], v[192:195], v[152:155]
	v_mfma_f32_16x16x32_bf16 v[132:135], v[68:71], v[200:203], v[132:135]
	v_mfma_f32_16x16x32_bf16 v[128:131], v[98:101], v[200:203], v[128:131]
	s_barrier
	s_setprio 0
	s_add_i32 s96, 0, 0x14000
	s_add_i32 s29, s29, s18
	v_add_u32_e32 v96, s96, v225
	v_lshl_add_u64 v[106:107], s[84:85], 0, v[182:183]
	s_mov_b32 m0, s29
	ds_read_b128 v[228:231], v96
	ds_read_b128 v[232:235], v96 offset:1024
	ds_read_b128 v[236:239], v96 offset:2048
	ds_read_b128 v[240:243], v96 offset:3072
	global_load_lds_dwordx4 v182, s[84:85]
	v_lshl_add_u64 v[248:249], s[84:85], 0, v[186:187]
	s_add_i32 m0, s29, 0x2000
	s_nop 0
	global_load_lds_dwordx4 v186, s[84:85]
	s_setprio 1
	s_barrier
	s_waitcnt lgkmcnt(0)
	v_mfma_f32_16x16x32_bf16 v[164:167], v[228:231], v[102:105], 0
	v_mfma_f32_16x16x32_bf16 v[102:105], v[236:239], v[102:105], 0
	v_mfma_f32_16x16x32_bf16 v[120:123], v[228:231], v[196:199], 0
	s_mov_b32 m0, s2
	v_mfma_f32_16x16x32_bf16 v[116:119], v[236:239], v[196:199], 0
	v_lshl_add_u64 v[250:251], s[46:47], 0, v[176:177]
	v_mfma_f32_16x16x32_bf16 v[164:167], v[232:235], v[112:115], v[164:167]
	v_mfma_f32_16x16x32_bf16 v[102:105], v[240:243], v[112:115], v[102:105]
	v_mfma_f32_16x16x32_bf16 v[112:115], v[228:231], v[124:127], 0
	v_mfma_f32_16x16x32_bf16 v[124:127], v[236:239], v[124:127], 0
	v_mfma_f32_16x16x32_bf16 v[120:123], v[232:235], v[200:203], v[120:123]
	v_mfma_f32_16x16x32_bf16 v[116:119], v[240:243], v[200:203], v[116:119]
	v_mfma_f32_16x16x32_bf16 v[112:115], v[232:235], v[192:195], v[112:115]
	v_mfma_f32_16x16x32_bf16 v[124:127], v[240:243], v[192:195], v[124:127]
	s_barrier
	s_setprio 0
	ds_read_b128 v[144:147], v227 offset:16384
	ds_read_b128 v[148:151], v227 offset:17408
	ds_read_b128 v[160:163], v227 offset:18432
	ds_read_b128 v[192:195], v227 offset:19456
	ds_read_b128 v[196:199], v227 offset:20480
	ds_read_b128 v[200:203], v227 offset:21504
	global_load_lds_dwordx4 v176, s[46:47]
	v_lshl_add_u64 v[252:253], s[46:47], 0, v[184:185]
	s_mov_b32 m0, s3
	s_mov_b64 exec, s[98:99]
	global_load_lds_dwordx4 v184, s[46:47]
	s_mov_b64 exec, -1
	s_waitcnt vmcnt(10)
	s_setprio 1
	s_barrier
	s_waitcnt lgkmcnt(0)
	v_mfma_f32_16x16x32_bf16 v[88:91], v[56:59], v[144:147], 0
	v_mfma_f32_16x16x32_bf16 v[84:87], v[80:83], v[144:147], 0
	v_mfma_f32_16x16x32_bf16 v[52:55], v[56:59], v[160:163], 0
	v_mfma_f32_16x16x32_bf16 v[48:51], v[80:83], v[160:163], 0
	v_mfma_f32_16x16x32_bf16 v[28:31], v[56:59], v[196:199], 0
	v_mfma_f32_16x16x32_bf16 v[24:27], v[80:83], v[196:199], 0
	v_mfma_f32_16x16x32_bf16 v[88:91], v[68:71], v[148:151], v[88:91]
	v_mfma_f32_16x16x32_bf16 v[84:87], v[98:101], v[148:151], v[84:87]
	v_mfma_f32_16x16x32_bf16 v[52:55], v[68:71], v[192:195], v[52:55]
	v_mfma_f32_16x16x32_bf16 v[48:51], v[98:101], v[192:195], v[48:51]
	v_mfma_f32_16x16x32_bf16 v[28:31], v[68:71], v[200:203], v[28:31]
	v_mfma_f32_16x16x32_bf16 v[24:27], v[98:101], v[200:203], v[24:27]
	s_barrier
	s_setprio 0
	v_add_u32_e32 v96, 0x18000, v225
	ds_read_b128 v[80:83], v96 offset:2048
	ds_read_b128 v[98:101], v96 offset:3072
	s_add_u32 s84, s84, s57
	s_addc_u32 s85, s85, 0
	s_add_i32 s29, s96, s18
	v_lshl_add_u64 v[218:219], s[84:85], 0, v[182:183]
	s_mov_b32 m0, s29
	v_lshl_add_u64 v[220:221], s[84:85], 0, v[186:187]
	global_load_lds_dwordx4 v182, s[84:85]
	s_add_i32 m0, s29, 0x2000
	s_nop 0
	global_load_lds_dwordx4 v186, s[84:85]
	s_waitcnt vmcnt(6)
	s_setprio 1
	s_barrier
	v_mfma_f32_16x16x32_bf16 v[44:47], v[228:231], v[160:163], 0
	v_mfma_f32_16x16x32_bf16 v[40:43], v[236:239], v[160:163], 0
	v_mfma_f32_16x16x32_bf16 v[20:23], v[228:231], v[196:199], 0
	s_add_i32 s29, 0, 0x18000
	v_mfma_f32_16x16x32_bf16 v[16:19], v[236:239], v[196:199], 0
	v_add_u32_e32 v96, s29, v225
	v_mfma_f32_16x16x32_bf16 v[56:59], v[228:231], v[144:147], 0
	v_mfma_f32_16x16x32_bf16 v[68:71], v[236:239], v[144:147], 0
	v_mfma_f32_16x16x32_bf16 v[44:47], v[232:235], v[192:195], v[44:47]
	v_mfma_f32_16x16x32_bf16 v[40:43], v[240:243], v[192:195], v[40:43]
	v_mfma_f32_16x16x32_bf16 v[20:23], v[232:235], v[200:203], v[20:23]
	v_mfma_f32_16x16x32_bf16 v[16:19], v[240:243], v[200:203], v[16:19]
	v_mfma_f32_16x16x32_bf16 v[56:59], v[232:235], v[148:151], v[56:59]
	v_mfma_f32_16x16x32_bf16 v[68:71], v[240:243], v[148:151], v[68:71]
	s_barrier
	s_setprio 0
	ds_read_b128 v[72:75], v96
	ds_read_b128 v[76:79], v96 offset:1024
	s_add_u32 s46, s46, s64
	s_addc_u32 s47, s47, 0
	s_mov_b32 m0, s4
	ds_read_b128 v[144:147], v227 offset:32768
	ds_read_b128 v[148:151], v227 offset:33792
	ds_read_b128 v[192:195], v227 offset:34816
	ds_read_b128 v[196:199], v227 offset:35840
	ds_read_b128 v[200:203], v227 offset:36864
	ds_read_b128 v[228:231], v227 offset:37888
	global_load_lds_dwordx4 v176, s[46:47]
	s_mov_b32 m0, s5
	s_mov_b64 exec, s[98:99]
	global_load_lds_dwordx4 v184, s[46:47]
	s_mov_b64 exec, -1
	s_waitcnt lgkmcnt(6)
	s_setprio 1
	s_barrier
	s_waitcnt lgkmcnt(0)
	v_mfma_f32_16x16x32_bf16 v[160:163], v[72:75], v[144:147], v[172:175]
	v_mfma_f32_16x16x32_bf16 v[172:175], v[76:79], v[148:151], v[160:163]
	v_mfma_f32_16x16x32_bf16 v[160:163], v[80:83], v[144:147], v[168:171]
	v_mfma_f32_16x16x32_bf16 v[156:159], v[72:75], v[192:195], v[156:159]
	v_mfma_f32_16x16x32_bf16 v[152:155], v[80:83], v[192:195], v[152:155]
	v_mfma_f32_16x16x32_bf16 v[132:135], v[72:75], v[200:203], v[132:135]
	v_mfma_f32_16x16x32_bf16 v[128:131], v[80:83], v[200:203], v[128:131]
	v_mfma_f32_16x16x32_bf16 v[168:171], v[98:101], v[148:151], v[160:163]
	v_mfma_f32_16x16x32_bf16 v[156:159], v[76:79], v[196:199], v[156:159]
	v_mfma_f32_16x16x32_bf16 v[152:155], v[98:101], v[196:199], v[152:155]
	v_mfma_f32_16x16x32_bf16 v[132:135], v[76:79], v[228:231], v[132:135]
	v_mfma_f32_16x16x32_bf16 v[128:131], v[98:101], v[228:231], v[128:131]
	s_barrier
	s_setprio 0
	s_add_i32 s46, 0, 0x1c000
	s_add_i32 s29, s29, s18
	v_add_u32_e32 v96, s46, v225
	v_lshl_add_u64 v[106:107], v[106:107], 0, s[6:7]
	s_mov_b32 m0, s29
	ds_read_b128 v[232:235], v96
	ds_read_b128 v[236:239], v96 offset:1024
	ds_read_b128 v[240:243], v96 offset:2048
	ds_read_b128 v[244:247], v96 offset:3072
	global_load_lds_dwordx4 v[106:107], off
	v_lshl_add_u64 v[106:107], v[248:249], 0, s[6:7]
	s_add_i32 m0, s29, 0x2000
	s_nop 0
	global_load_lds_dwordx4 v[106:107], off
	s_setprio 1
	s_barrier
	s_waitcnt lgkmcnt(0)
	v_mfma_f32_16x16x32_bf16 v[160:163], v[232:235], v[144:147], v[164:167]
	v_mfma_f32_16x16x32_bf16 v[102:105], v[240:243], v[144:147], v[102:105]
	v_mfma_f32_16x16x32_bf16 v[164:167], v[236:239], v[148:151], v[160:163]
	s_mov_b32 m0, s88
	v_mfma_f32_16x16x32_bf16 v[160:163], v[244:247], v[148:151], v[102:105]
	v_lshl_add_u64 v[106:107], v[250:251], 0, s[6:7]
	v_mfma_f32_16x16x32_bf16 v[102:105], v[232:235], v[192:195], v[112:115]
	v_mfma_f32_16x16x32_bf16 v[148:151], v[236:239], v[196:199], v[102:105]
	v_mfma_f32_16x16x32_bf16 v[102:105], v[240:243], v[192:195], v[124:127]
	v_mfma_f32_16x16x32_bf16 v[144:147], v[244:247], v[196:199], v[102:105]
	v_mfma_f32_16x16x32_bf16 v[102:105], v[232:235], v[200:203], v[120:123]
	v_mfma_f32_16x16x32_bf16 v[120:123], v[236:239], v[228:231], v[102:105]
	v_mfma_f32_16x16x32_bf16 v[102:105], v[240:243], v[200:203], v[116:119]
	v_mfma_f32_16x16x32_bf16 v[116:119], v[244:247], v[228:231], v[102:105]
	s_barrier
	s_setprio 0
	s_nop 2
	ds_read_b128 v[102:105], v227 offset:49152
	ds_read_b128 v[112:115], v227 offset:50176
	ds_read_b128 v[124:127], v227 offset:51200
	ds_read_b128 v[192:195], v227 offset:52224
	ds_read_b128 v[196:199], v227 offset:53248
	ds_read_b128 v[200:203], v227 offset:54272
	global_load_lds_dwordx4 v[106:107], off
	v_lshl_add_u64 v[106:107], v[252:253], 0, s[6:7]
	s_mov_b32 m0, s89
	s_mov_b64 exec, s[98:99]
	global_load_lds_dwordx4 v[106:107], off
	s_mov_b64 exec, -1
	s_waitcnt vmcnt(10)
	s_setprio 1
	s_barrier
	s_waitcnt lgkmcnt(0)
	v_mfma_f32_16x16x32_bf16 v[88:91], v[72:75], v[102:105], v[88:91]
	v_mfma_f32_16x16x32_bf16 v[84:87], v[80:83], v[102:105], v[84:87]
	v_mfma_f32_16x16x32_bf16 v[52:55], v[72:75], v[124:127], v[52:55]
	v_mfma_f32_16x16x32_bf16 v[48:51], v[80:83], v[124:127], v[48:51]
	v_mfma_f32_16x16x32_bf16 v[28:31], v[72:75], v[196:199], v[28:31]
	v_mfma_f32_16x16x32_bf16 v[24:27], v[80:83], v[196:199], v[24:27]
	v_mfma_f32_16x16x32_bf16 v[88:91], v[76:79], v[112:115], v[88:91]
	v_mfma_f32_16x16x32_bf16 v[84:87], v[98:101], v[112:115], v[84:87]
	v_mfma_f32_16x16x32_bf16 v[52:55], v[76:79], v[192:195], v[52:55]
	v_mfma_f32_16x16x32_bf16 v[48:51], v[98:101], v[192:195], v[48:51]
	v_mfma_f32_16x16x32_bf16 v[28:31], v[76:79], v[200:203], v[28:31]
	v_mfma_f32_16x16x32_bf16 v[24:27], v[98:101], v[200:203], v[24:27]
	s_barrier
	s_setprio 0
	v_add_u32_e32 v96, 0x10000, v225
	ds_read_b128 v[80:83], v96 offset:2048
	ds_read_b128 v[98:101], v96 offset:3072
	s_add_i32 s29, s46, s18
	v_lshl_add_u64 v[72:73], v[218:219], 0, s[6:7]
	s_mov_b32 m0, s29
	s_nop 0
	global_load_lds_dwordx4 v[72:73], off
	v_lshl_add_u64 v[72:73], v[220:221], 0, s[6:7]
	s_add_i32 m0, s29, 0x2000
	s_nop 0
	global_load_lds_dwordx4 v[72:73], off
	s_waitcnt vmcnt(6)
	s_setprio 1
	s_barrier
	v_mfma_f32_16x16x32_bf16 v[56:59], v[232:235], v[102:105], v[56:59]
	v_mfma_f32_16x16x32_bf16 v[76:79], v[236:239], v[112:115], v[56:59]
	v_mfma_f32_16x16x32_bf16 v[56:59], v[240:243], v[102:105], v[68:71]
	s_add_u32 s44, s44, 0x100
	v_mfma_f32_16x16x32_bf16 v[44:47], v[232:235], v[124:127], v[44:47]
	s_addc_u32 s45, s45, 0
	v_mfma_f32_16x16x32_bf16 v[40:43], v[240:243], v[124:127], v[40:43]
	s_add_u32 s87, s87, 0x100
	v_mfma_f32_16x16x32_bf16 v[20:23], v[232:235], v[196:199], v[20:23]
	s_addc_u32 vcc_lo, vcc_lo, 0
	v_mfma_f32_16x16x32_bf16 v[16:19], v[240:243], v[196:199], v[16:19]
	s_cmp_ge_u32 vcc_hi, s37
	v_mfma_f32_16x16x32_bf16 v[72:75], v[244:247], v[112:115], v[56:59]
	s_mov_b32 s46, vcc_hi
	v_mfma_f32_16x16x32_bf16 v[44:47], v[236:239], v[192:195], v[44:47]
	v_mfma_f32_16x16x32_bf16 v[40:43], v[244:247], v[192:195], v[40:43]
	v_mfma_f32_16x16x32_bf16 v[20:23], v[236:239], v[200:203], v[20:23]
	v_mfma_f32_16x16x32_bf16 v[16:19], v[244:247], v[200:203], v[16:19]
	s_barrier
	s_setprio 0
